# P4 fast path + hgrn_a epilogue: P^T tile transposed through per-wave LDS, 4 coalesced dwordx4 stores
# speedup vs baseline: 1.0037x; 1.0037x over previous
; __device__ __forceinline__ void hgrn_a_load(Ctx& X, int u, RawA& R) {
;     const int hd = u & 7, c = u >> 3, t0 = c * 64, seg = X.tid >> 7, k = X.tid & 127;
;     const bf16_t* HLF = (const bf16_t*)(X.ws + WS_PROJ) + 4 * TSZ; const bf16_t* HV = (const bf16_t*)(X.ws + WS_PROJ) + 5 * TSZ;
; #pragma unroll
;     for (int i = 0; i < 16; ++i) { const size_t off = (size_t)(t0 + 16 * seg + i) * 1024 + hd * 128 + k; R.lf[i] = HLF[off]; R.vv[i] = HV[off]; }
; }
; __global__ void __launch_bounds__(512, 2) fwd_mega(Args a) {
;     ...
;             RawA cur; hgrn_a_load(X, blockIdx.x, cur);
;             for (int u = blockIdx.x; u < 2048; u += X.G) { RawA nxt = cur; if (u + X.G < 2048) hgrn_a_load(X, u + X.G, nxt); hgrn_a_compute(X, u, cur); cur = nxt; }
.LBB0_463:
	s_cmp_lt_i32 s92, 4
	s_cselect_b64 s[2:3], -1, 0
	s_and_b64 s[34:35], s[2:3], s[0:1]
	s_andn2_b64 vcc, exec, s[34:35]
	s_cbranch_vccnz .LBB0_616
	v_readlane_b32 s0, v245, 0
	s_cmpk_gt_i32 s0, 0x7ff
	v_readlane_b32 s1, v245, 1
	s_cbranch_scc1 .LBB0_471
	s_add_u32 s10, s90, 0x13700000
	s_addc_u32 s11, s91, 0
	s_add_u32 s12, s90, 0x15700000
	v_lshrrev_b32_e32 v0, 3, v209
	s_addc_u32 s13, s91, 0
	v_and_b32_e32 v41, 0x70, v0
	s_and_b32 s0, s54, 0xffffffc0
	v_readlane_b32 s20, v245, 0
	v_add_u32_e32 v20, s0, v41
	s_lshl_b32 s0, s20, 7
	v_and_b32_e32 v40, 0x7f, v209
	v_or_b32_e32 v0, 15, v20
	s_and_b32 s0, s0, 0x380
	v_ashrrev_i32_e32 v1, 31, v0
	v_or_b32_e32 v2, s0, v40
	v_lshlrev_b64 v[0:1], 11, v[0:1]
	v_lshlrev_b32_e32 v44, 1, v2
	v_or_b32_e32 v0, v0, v44
	v_lshl_add_u64 v[4:5], s[12:13], 0, v[0:1]
	v_lshl_add_u64 v[8:9], s[10:11], 0, v[0:1]
	v_or_b32_e32 v0, 14, v20
	v_ashrrev_i32_e32 v1, 31, v0
	v_lshlrev_b64 v[0:1], 11, v[0:1]
	v_or_b32_e32 v0, v0, v44
	v_lshl_add_u64 v[12:13], s[12:13], 0, v[0:1]
	v_lshl_add_u64 v[14:15], s[10:11], 0, v[0:1]
	v_or_b32_e32 v0, 13, v20
	v_ashrrev_i32_e32 v1, 31, v0
	v_lshlrev_b64 v[0:1], 11, v[0:1]
	v_or_b32_e32 v0, v0, v44
	v_lshl_add_u64 v[16:17], s[12:13], 0, v[0:1]
	v_lshl_add_u64 v[18:19], s[10:11], 0, v[0:1]
	v_or_b32_e32 v0, 12, v20
	v_ashrrev_i32_e32 v1, 31, v0
	v_lshlrev_b64 v[0:1], 11, v[0:1]
	v_or_b32_e32 v0, v0, v44
	v_lshl_add_u64 v[22:23], s[12:13], 0, v[0:1]
	v_lshl_add_u64 v[24:25], s[10:11], 0, v[0:1]
	global_load_ushort v2, v[4:5], off
	global_load_ushort v6, v[8:9], off
	global_load_ushort v3, v[12:13], off
	global_load_ushort v7, v[14:15], off
	global_load_ushort v1, v[16:17], off
	global_load_ushort v10, v[18:19], off
	global_load_ushort v0, v[22:23], off
	global_load_ushort v11, v[24:25], off
	v_or_b32_e32 v4, 11, v20
	v_ashrrev_i32_e32 v5, 31, v4
	v_lshlrev_b64 v[4:5], 11, v[4:5]
	v_or_b32_e32 v4, v4, v44
	v_lshl_add_u64 v[12:13], s[12:13], 0, v[4:5]
	v_lshl_add_u64 v[22:23], s[10:11], 0, v[4:5]
	v_or_b32_e32 v4, 10, v20
	v_ashrrev_i32_e32 v5, 31, v4
	v_lshlrev_b64 v[4:5], 11, v[4:5]
	v_or_b32_e32 v4, v4, v44
	v_lshl_add_u64 v[24:25], s[12:13], 0, v[4:5]
	v_lshl_add_u64 v[26:27], s[10:11], 0, v[4:5]
	v_or_b32_e32 v4, 9, v20
	v_ashrrev_i32_e32 v5, 31, v4
	v_lshlrev_b64 v[4:5], 11, v[4:5]
	v_or_b32_e32 v4, v4, v44
	v_lshl_add_u64 v[28:29], s[12:13], 0, v[4:5]
	v_lshl_add_u64 v[30:31], s[10:11], 0, v[4:5]
	v_or_b32_e32 v4, 8, v20
	v_ashrrev_i32_e32 v5, 31, v4
	v_lshlrev_b64 v[4:5], 11, v[4:5]
	v_or_b32_e32 v4, v4, v44
	v_lshl_add_u64 v[32:33], s[12:13], 0, v[4:5]
	v_lshl_add_u64 v[34:35], s[10:11], 0, v[4:5]
	global_load_ushort v4, v[12:13], off
	global_load_ushort v14, v[22:23], off
	global_load_ushort v5, v[24:25], off
	global_load_ushort v15, v[26:27], off
	global_load_ushort v8, v[28:29], off
	global_load_ushort v16, v[30:31], off
	global_load_ushort v9, v[32:33], off
	global_load_ushort v19, v[34:35], off
	v_or_b32_e32 v12, 7, v20
	v_ashrrev_i32_e32 v13, 31, v12
	v_lshlrev_b64 v[12:13], 11, v[12:13]
	v_or_b32_e32 v12, v12, v44
	v_lshl_add_u64 v[26:27], s[12:13], 0, v[12:13]
	v_lshl_add_u64 v[28:29], s[10:11], 0, v[12:13]
	v_or_b32_e32 v12, 6, v20
	v_ashrrev_i32_e32 v13, 31, v12
	v_lshlrev_b64 v[12:13], 11, v[12:13]
	v_or_b32_e32 v12, v12, v44
	v_lshl_add_u64 v[30:31], s[12:13], 0, v[12:13]
	v_lshl_add_u64 v[32:33], s[10:11], 0, v[12:13]
	v_or_b32_e32 v12, 5, v20
	v_ashrrev_i32_e32 v13, 31, v12
	v_lshlrev_b64 v[12:13], 11, v[12:13]
	v_or_b32_e32 v12, v12, v44
	v_lshl_add_u64 v[34:35], s[12:13], 0, v[12:13]
	v_lshl_add_u64 v[36:37], s[10:11], 0, v[12:13]
	v_or_b32_e32 v12, 4, v20
	v_ashrrev_i32_e32 v13, 31, v12
	v_lshlrev_b64 v[12:13], 11, v[12:13]
	v_or_b32_e32 v12, v12, v44
	v_lshl_add_u64 v[38:39], s[12:13], 0, v[12:13]
	v_lshl_add_u64 v[42:43], s[10:11], 0, v[12:13]
	global_load_ushort v12, v[26:27], off
	global_load_ushort v22, v[28:29], off
	global_load_ushort v13, v[30:31], off
	global_load_ushort v23, v[32:33], off
	global_load_ushort v17, v[34:35], off
	global_load_ushort v24, v[36:37], off
	global_load_ushort v18, v[38:39], off
	global_load_ushort v25, v[42:43], off
	v_or_b32_e32 v26, 3, v20
	v_ashrrev_i32_e32 v27, 31, v26
	v_lshlrev_b64 v[26:27], 11, v[26:27]
	v_or_b32_e32 v26, v26, v44
	v_lshl_add_u64 v[28:29], s[12:13], 0, v[26:27]
	v_lshl_add_u64 v[32:33], s[10:11], 0, v[26:27]
	v_or_b32_e32 v26, 2, v20
	v_ashrrev_i32_e32 v27, 31, v26
	v_lshlrev_b64 v[30:31], 11, v[26:27]
	v_or_b32_e32 v26, 1, v20
	v_ashrrev_i32_e32 v27, 31, v26
	v_lshlrev_b64 v[36:37], 11, v[26:27]
	v_ashrrev_i32_e32 v21, 31, v20
	v_or_b32_e32 v30, v30, v44
	v_or_b32_e32 v36, v36, v44
	v_lshlrev_b64 v[42:43], 11, v[20:21]
	v_lshl_add_u64 v[34:35], s[12:13], 0, v[30:31]
	v_lshl_add_u64 v[38:39], s[12:13], 0, v[36:37]
	v_or_b32_e32 v42, v42, v44
	v_lshl_add_u64 v[44:45], s[12:13], 0, v[42:43]
	global_load_ushort v20, v[28:29], off
	global_load_ushort v21, v[34:35], off
	global_load_ushort v26, v[38:39], off
	global_load_ushort v27, v[44:45], off
	v_lshl_add_u64 v[34:35], s[10:11], 0, v[30:31]
	v_lshl_add_u64 v[36:37], s[10:11], 0, v[36:37]
	v_lshl_add_u64 v[38:39], s[10:11], 0, v[42:43]
	global_load_ushort v28, v[32:33], off
	global_load_ushort v29, v[34:35], off
	global_load_ushort v30, v[36:37], off
	global_load_ushort v31, v[38:39], off
	s_movk_i32 s2, 0xff
	v_cmp_lt_u32_e64 s[4:5], s2, v209
	s_movk_i32 s2, 0x17f
	v_lshl_add_u32 v43, v40, 2, 0
	v_cmp_lt_u32_e64 s[6:7], s2, v209
	s_movk_i32 s2, 0x1ff
	v_mul_u32_u24_e32 v32, 0x8c, v40
	v_lshlrev_b32_e32 v33, 1, v41
	v_readlane_b32 s14, v245, 21
	v_cmp_lt_u32_e64 s[8:9], s2, v209
	v_add3_u32 v44, v43, v32, v33
	v_lshrrev_b32_e32 v32, 5, v208
	v_and_b32_e32 v34, 31, v209
	s_lshr_b32 s2, s14, 7
	s_and_b32 s16, s14, 64
	v_lshl_or_b32 v33, s2, 5, v34
	v_lshl_add_u32 v46, v32, 4, 0
	s_movk_i32 s14, 0x90
	v_lshlrev_b32_e32 v38, 4, v32
	v_mad_u64_u32 v[32:33], s[14:15], v33, s14, v[46:47]
	v_or_b32_e32 v33, s16, v34
	v_mul_u32_u24_e32 v45, 0x90, v33
	v_or_b32_e32 v33, 32, v33
	v_mul_u32_u24_e32 v47, 0x90, v33
	v_lshlrev_b32_e32 v33, 7, v34
	v_lshl_or_b32 v34, s2, 12, v33
	v_ashrrev_i32_e32 v35, 31, v34
	v_lshl_add_u64 v[34:35], v[34:35], 1, s[88:89]
	v_mov_b32_e32 v39, 0
	v_readlane_b32 s21, v245, 1
	s_mov_b32 s3, 0
	v_lshl_add_u64 v[34:35], v[34:35], 0, v[38:39]
	s_lshl_b32 s2, s16, 1
	v_lshl_add_u64 v[34:35], v[34:35], 0, s[2:3]
	s_add_i32 s2, s20, s94
	s_ashr_i32 s21, s20, 31
	s_lshl_b32 s26, s2, 3
	s_lshl_b32 s27, s2, 7
	s_lshl_b32 s28, s94, 7
	s_ashr_i32 s15, s94, 31
	s_lshl_b64 s[2:3], s[20:21], 9
	s_add_u32 s2, s90, s2
	v_lshlrev_b32_e32 v36, 2, v209
	v_mov_b32_e32 v37, v39
	s_addc_u32 s3, s91, s3
	v_add_u32_e32 v42, 0, v36
	v_lshl_add_u64 v[36:37], s[2:3], 0, v[36:37]
	s_mov_b64 s[2:3], 0x4700000
	s_movk_i32 s0, 0x80
	s_mov_b32 s14, s94
	v_lshl_add_u64 v[36:37], v[36:37], 0, s[2:3]
	s_mov_b32 s2, s20
	v_cmp_gt_u32_e64 s[0:1], s0, v209
	s_lshl_b64 s[16:17], s[14:15], 9
	v_add_u32_e32 v33, v46, v45
	v_add_u32_e32 v45, v46, v47
	s_mov_b64 s[18:19], s[20:21]
	v_writelane_b32 v245, s2, 0
	s_waitcnt vmcnt(0)
; #define LAS __attribute__((address_space(3)))
; __device__ __forceinline__ unsigned pk2_rne(float lo, float hi) { const f32x2_t f = {lo, hi}; return __builtin_bit_cast(unsigned, __builtin_convertvector(f, bf16x2_t)); }
; #define MFMA32(a, b, c) __builtin_amdgcn_mfma_f32_32x32x16_bf16((a), (b), (c), 0, 0, 0)
; __device__ __forceinline__ void hgrn_a_compute(Ctx& X, int u, const RawA& R) {
;     ...
;     const int vt = w >> 1, kt2 = 2 * (w & 1);
;     f32x16 acc[2];
; #pragma unroll
;     for (int e = 0; e < 2; ++e)
; #pragma unroll
;         for (int i = 0; i < 16; ++i) acc[e][i] = 0.f;
; #pragma unroll
;     for (int ks = 0; ks < 4; ++ks) {
;         const bf16x8 bfr = *(const LAS bf16x8*)(VT + (32 * vt + r) * 72 + 16 * ks + 8 * h);
; #pragma unroll
;         for (int e = 0; e < 2; ++e) { const bf16x8 af = *(const LAS bf16x8*)(KT + (32 * (kt2 + e) + r) * 72 + 16 * ks + 8 * h); acc[e] = MFMA32(af, bfr, acc[e]); }
;     }
;     bf16_t* P = (bf16_t*)X.out + (size_t)u * 16384;
; #pragma unroll
;     for (int e = 0; e < 2; ++e)
; #pragma unroll
;         for (int g = 0; g < 4; ++g) {
;             { u32x2 pw; pw.x = pk2_rne(acc[e][4 * g], acc[e][4 * g + 1]); pw.y = pk2_rne(acc[e][4 * g + 2], acc[e][4 * g + 3]);
;               *(u32x2*)(P + (32 * vt + r) * 128 + 32 * (kt2 + e) + 8 * g + 4 * h) = pw; }
;         }
	v_mov_b32_e32 v73, v2
	v_mov_b32_e32 v72, v3
	v_mov_b32_e32 v71, v1
	v_mov_b32_e32 v70, v0
	v_mov_b32_e32 v65, v4
	v_mov_b32_e32 v64, v5
	v_mov_b32_e32 v63, v8
	v_mov_b32_e32 v62, v9
	v_mov_b32_e32 v57, v12
	v_mov_b32_e32 v56, v13
	v_mov_b32_e32 v55, v17
	v_mov_b32_e32 v54, v18
	v_mov_b32_e32 v77, v6
	v_mov_b32_e32 v49, v20
	v_mov_b32_e32 v48, v21
	v_mov_b32_e32 v47, v26
	v_mov_b32_e32 v46, v27
	v_mov_b32_e32 v76, v7
	v_mov_b32_e32 v75, v10
	v_mov_b32_e32 v74, v11
	v_mov_b32_e32 v69, v14
	v_mov_b32_e32 v68, v15
	v_mov_b32_e32 v67, v16
	v_mov_b32_e32 v66, v19
	v_mov_b32_e32 v61, v22
	v_mov_b32_e32 v60, v23
	v_mov_b32_e32 v59, v24
	v_mov_b32_e32 v58, v25
	v_mov_b32_e32 v53, v28
	v_mov_b32_e32 v52, v29
	v_mov_b32_e32 v51, v30
	v_mov_b32_e32 v50, v31
	v_writelane_b32 v245, s3, 1
	v_lshrrev_b32_e32 v100, 6, v209
	v_mul_u32_u24_e32 v100, 0x1200, v100
	v_add_u32_e32 v100, 0xa000, v100
	v_and_b32_e32 v101, 31, v209
	v_mul_u32_u24_e32 v101, 0x90, v101
	v_bfe_u32 v102, v209, 5, 1
	v_lshl_add_u32 v101, v102, 3, v101
	v_add_u32_e32 v108, v100, v101
	v_bfe_u32 v101, v209, 3, 3
	v_and_b32_e32 v102, 7, v209
	v_mul_u32_u24_e32 v103, 0x90, v101
	v_lshl_add_u32 v103, v102, 4, v103
	v_add_u32_e32 v109, v100, v103
	v_lshrrev_b32_e32 v103, 7, v209
	v_lshl_add_u32 v103, v103, 5, v101
	v_lshlrev_b32_e32 v103, 8, v103
	v_bfe_u32 v104, v209, 6, 1
	v_lshl_add_u32 v103, v104, 7, v103
	v_lshl_add_u32 v104, v102, 4, v103
	v_add_u32_e32 v104, 0x1000, v104
	v_mov_b32_e32 v105, 0
	v_lshl_add_u64 v[106:107], s[88:89], 0, v[104:105]
	s_branch .LBB0_467
.LBB0_466:
	s_or_b64 exec, exec, s[24:25]
	s_waitcnt lgkmcnt(0)
	s_barrier
	ds_read_b128 v[0:3], v33
	ds_read_b128 v[4:7], v32 offset:18432
	ds_read_b128 v[78:81], v32 offset:18464
	ds_read_b128 v[82:85], v33 offset:32
	s_waitcnt lgkmcnt(2)
	v_mfma_f32_32x32x16_bf16 v[16:31], v[0:3], v[4:7], 0
	ds_read_b128 v[0:3], v45
	ds_read_b128 v[86:89], v45 offset:32
	v_lshlrev_b64 v[38:39], 15, v[38:39]
	v_lshl_add_u64 v[110:111], v[106:107], 0, v[38:39]
	v_lshl_add_u64 v[38:39], v[34:35], 0, v[38:39]
	s_add_i32 s26, s26, s50
	s_add_i32 s27, s27, s28
	s_add_u32 s18, s18, s14
	s_addc_u32 s19, s19, s15
	s_waitcnt lgkmcnt(1)
	v_mfma_f32_32x32x16_bf16 v[0:15], v[0:3], v[4:7], 0
	v_lshl_add_u64 v[36:37], v[36:37], 0, s[16:17]
	s_and_b64 vcc, exec, s[22:23]
	s_mov_b32 s20, s2
	v_mfma_f32_32x32x16_bf16 v[16:31], v[82:85], v[78:81], v[16:31]
	s_waitcnt lgkmcnt(0)
	v_mfma_f32_32x32x16_bf16 v[0:15], v[86:89], v[78:81], v[0:15]
	ds_read_b128 v[78:81], v33 offset:64
	ds_read_b128 v[82:85], v32 offset:18496
	ds_read_b128 v[86:89], v32 offset:18528
	ds_read_b128 v[90:93], v33 offset:96
	s_waitcnt lgkmcnt(2)
	v_mfma_f32_32x32x16_bf16 v[16:31], v[78:81], v[82:85], v[16:31]
	ds_read_b128 v[78:81], v45 offset:64
	ds_read_b128 v[94:97], v45 offset:96
	s_waitcnt lgkmcnt(1)
	v_mfma_f32_32x32x16_bf16 v[0:15], v[78:81], v[82:85], v[0:15]
	v_mfma_f32_32x32x16_bf16 v[16:31], v[90:93], v[86:89], v[16:31]
	s_waitcnt lgkmcnt(0)
	v_mfma_f32_32x32x16_bf16 v[0:15], v[94:97], v[86:89], v[0:15]
	s_nop 9
	v_cvt_pk_bf16_f32 v16, v16, v17
	v_cvt_pk_bf16_f32 v17, v18, v19
	v_cvt_pk_bf16_f32 v18, v20, v21
	v_cvt_pk_bf16_f32 v19, v22, v23
	v_cvt_pk_bf16_f32 v20, v24, v25
	v_cvt_pk_bf16_f32 v21, v26, v27
	v_cvt_pk_bf16_f32 v22, v28, v29
	v_cvt_pk_bf16_f32 v23, v30, v31
	ds_write_b64 v108, v[16:17]
	ds_write_b64 v108, v[18:19] offset:16
	v_cvt_pk_bf16_f32 v0, v0, v1
	v_cvt_pk_bf16_f32 v1, v2, v3
	v_cvt_pk_bf16_f32 v2, v4, v5
	v_cvt_pk_bf16_f32 v3, v6, v7
	ds_write_b64 v108, v[20:21] offset:32
	ds_write_b64 v108, v[22:23] offset:48
	v_cvt_pk_bf16_f32 v4, v8, v9
	v_cvt_pk_bf16_f32 v5, v10, v11
	v_cvt_pk_bf16_f32 v6, v12, v13
	v_cvt_pk_bf16_f32 v7, v14, v15
	ds_write_b64 v108, v[0:1] offset:64
	ds_write_b64 v108, v[2:3] offset:80
	ds_write_b64 v108, v[4:5] offset:96
	ds_write_b64 v108, v[6:7] offset:112
	s_waitcnt lgkmcnt(0)
	ds_read_b128 v[16:19], v109
	ds_read_b128 v[20:23], v109 offset:1152
	ds_read_b128 v[0:3], v109 offset:2304
	ds_read_b128 v[4:7], v109 offset:3456
	s_waitcnt lgkmcnt(2)
	global_store_dwordx4 v[110:111], v[16:19], off offset:-4096
	global_store_dwordx4 v[110:111], v[20:23], off offset:-2048
	s_waitcnt lgkmcnt(0)
	global_store_dwordx4 v[110:111], v[0:3], off
	global_store_dwordx4 v[110:111], v[4:7], off offset:2048
	s_waitcnt vmcnt(4)
	s_nop 1
	v_mov_b32_e32 v2, v73
	v_mov_b32_e32 v3, v72
	v_mov_b32_e32 v1, v71
	v_mov_b32_e32 v0, v70
	v_mov_b32_e32 v4, v65
	v_mov_b32_e32 v5, v64
	v_mov_b32_e32 v8, v63
	v_mov_b32_e32 v9, v62
	v_mov_b32_e32 v12, v57
	v_mov_b32_e32 v13, v56
	v_mov_b32_e32 v17, v55
	v_mov_b32_e32 v18, v54
	v_mov_b32_e32 v20, v49
	v_mov_b32_e32 v21, v48
	v_mov_b32_e32 v26, v47
	v_mov_b32_e32 v27, v46
	v_mov_b32_e32 v6, v77
	v_mov_b32_e32 v7, v76
	v_mov_b32_e32 v10, v75
	v_mov_b32_e32 v11, v74
	v_mov_b32_e32 v14, v69
	v_mov_b32_e32 v15, v68
	v_mov_b32_e32 v16, v67
	v_mov_b32_e32 v31, v50
	v_mov_b32_e32 v30, v51
	v_mov_b32_e32 v29, v52
	v_mov_b32_e32 v28, v53
	v_mov_b32_e32 v25, v58
	v_mov_b32_e32 v24, v59
	v_mov_b32_e32 v23, v60
	v_mov_b32_e32 v22, v61
	v_mov_b32_e32 v19, v66
	s_barrier
	s_cbranch_vccnz .LBB0_471
